# idle-slot weight conversion with per-slot tile counts capped to fit the idle window (1500 tiles per GU slot), in_proj(L1) slot used
# baseline (speedup 1.0000x reference)
.LBB0_250:
	s_cmp_lg_u32 s96, 0x100
	s_cbranch_scc1 .Lic2_no
	s_cmp_lt_u32 s2, 85
	s_cbranch_scc1 .Lic2_no
	v_writelane_b32 v253, s0, 0
	v_writelane_b32 v253, s1, 1
	v_writelane_b32 v253, s2, 2
	v_writelane_b32 v253, s3, 3
	v_writelane_b32 v253, s4, 4
	v_writelane_b32 v253, s5, 5
	v_writelane_b32 v253, s6, 6
	v_writelane_b32 v253, s7, 7
	v_writelane_b32 v253, s8, 8
	v_writelane_b32 v253, s9, 9
	v_writelane_b32 v253, s10, 10
	v_writelane_b32 v253, s11, 11
	v_writelane_b32 v253, s12, 12
	v_writelane_b32 v253, s13, 13
	v_writelane_b32 v253, s14, 14
	v_writelane_b32 v253, s15, 15
	v_writelane_b32 v253, s16, 16
	v_writelane_b32 v253, s17, 17
	v_writelane_b32 v253, s18, 18
	v_writelane_b32 v253, s19, 19
	v_writelane_b32 v253, s20, 20
	v_writelane_b32 v253, s21, 21
	v_writelane_b32 v253, s22, 22
	v_writelane_b32 v253, s23, 23
	v_writelane_b32 v253, s24, 24
	v_writelane_b32 v253, s25, 25
	v_writelane_b32 v253, s26, 26
	v_writelane_b32 v253, s27, 27
	v_writelane_b32 v253, s28, 28
	v_writelane_b32 v253, s29, 29
	v_writelane_b32 v253, s30, 30
	v_writelane_b32 v253, s31, 31
	v_writelane_b32 v253, s32, 32
	v_writelane_b32 v253, s33, 33
	v_writelane_b32 v253, s34, 34
	v_writelane_b32 v253, s35, 35
	v_writelane_b32 v253, s36, 36
	v_writelane_b32 v253, s37, 37
	v_writelane_b32 v253, s38, 38
	v_writelane_b32 v253, s39, 39
	v_writelane_b32 v253, s40, 40
	v_writelane_b32 v253, s41, 41
	v_writelane_b32 v253, s42, 42
	v_writelane_b32 v253, s43, 43
	v_writelane_b32 v253, s44, 44
	v_writelane_b32 v253, s45, 45
	v_writelane_b32 v253, s46, 46
	v_writelane_b32 v253, s47, 47
	v_writelane_b32 v253, s48, 48
	v_writelane_b32 v253, s49, 49
	v_writelane_b32 v253, s50, 50
	v_writelane_b32 v253, s51, 51
	v_writelane_b32 v253, s52, 52
	v_writelane_b32 v253, s53, 53
	v_writelane_b32 v253, s54, 54
	v_writelane_b32 v253, s55, 55
	v_writelane_b32 v253, s56, 56
	v_writelane_b32 v253, s57, 57
	v_writelane_b32 v253, s58, 58
	v_writelane_b32 v253, s59, 59
	v_writelane_b32 v253, s60, 60
	v_writelane_b32 v253, s61, 61
	v_writelane_b32 v253, s62, 62
	v_writelane_b32 v253, s63, 63
	v_writelane_b32 v254, s64, 0
	v_writelane_b32 v254, s65, 1
	v_writelane_b32 v254, s66, 2
	v_writelane_b32 v254, s67, 3
	v_writelane_b32 v254, s68, 4
	v_writelane_b32 v254, s69, 5
	v_writelane_b32 v254, s70, 6
	v_writelane_b32 v254, s71, 7
	v_writelane_b32 v254, s72, 8
	v_writelane_b32 v254, s73, 9
	v_writelane_b32 v254, s74, 10
	v_writelane_b32 v254, s75, 11
	v_writelane_b32 v254, s76, 12
	v_writelane_b32 v254, s77, 13
	v_writelane_b32 v254, s78, 14
	v_writelane_b32 v254, s79, 15
	v_writelane_b32 v254, s80, 16
	v_writelane_b32 v254, s81, 17
	v_writelane_b32 v254, s82, 18
	v_writelane_b32 v254, s83, 19
	v_writelane_b32 v254, s84, 20
	v_writelane_b32 v254, s85, 21
	v_writelane_b32 v254, s86, 22
	v_writelane_b32 v254, s87, 23
	v_writelane_b32 v254, s88, 24
	v_writelane_b32 v254, s89, 25
	v_writelane_b32 v254, s90, 26
	v_writelane_b32 v254, s91, 27
	v_writelane_b32 v254, s92, 28
	v_writelane_b32 v254, s93, 29
	v_writelane_b32 v254, s94, 30
	v_writelane_b32 v254, s95, 31
	v_writelane_b32 v254, s96, 32
	v_writelane_b32 v254, s97, 33
	v_writelane_b32 v254, s98, 34
	v_writelane_b32 v254, s99, 35
	v_readlane_b32 s0, v249, 62
	v_readlane_b32 s1, v248, 8
	s_cmp_eq_u32 s0, 1
	s_cbranch_scc0 .Lic2_c1
	s_mov_b32 s3, 0x0
	s_mov_b32 s101, 0x57f
	s_mov_b32 s52, 1
	s_branch .Lic2_go
.Lic2_c1:
	s_cmp_eq_u32 s0, 2
	s_cbranch_scc0 .Lic2_c2
	s_mov_b32 s3, 0x1138
	s_mov_b32 s101, 0x15df
	s_mov_b32 s52, 1
	s_branch .Lic2_go

.LnrmA_loop:
	s_mov_b32 s37, s36
	s_cmpk_gt_i32 s37, 0x207f
	s_cselect_b32 s43, 0x2080, 0
	s_cselect_b32 vcc_lo, 0x2000, 0
	s_cselect_b32 vcc_hi, 0x80, 0
	s_sub_i32 s43, s37, s43
	s_add_i32 vcc_lo, vcc_lo, s43
	s_addk_i32 vcc_lo, 0xff80
	s_add_i32 vcc_hi, vcc_hi, s43
	s_cmpk_lt_i32 s43, 0x80
	s_cselect_b32 vcc_lo, vcc_hi, vcc_lo
	s_cselect_b32 s0, s40, s92
	s_cselect_b32 s1, s41, s93
	s_lshl_b32 vcc_lo, vcc_lo, 12
	s_lshl_b32 vcc_hi, s37, 11
	v_add_u32_e32 v114, vcc_lo, v106
	v_add_u32_e32 v117, vcc_hi, v107
	global_load_dwordx2 v[16:17], v117, s[4:5] nt
	global_load_dwordx2 v[18:19], v117, s[4:5] offset:512 nt
	global_load_dwordx2 v[20:21], v117, s[4:5] offset:1024 nt
	global_load_dwordx2 v[22:23], v117, s[4:5] offset:1536 nt
	global_load_dwordx4 v[0:3], v114, s[0:1] nt
	global_load_dwordx4 v[4:7], v114, s[0:1] offset:1024 nt
	global_load_dwordx4 v[8:11], v114, s[0:1] offset:2048 nt
	global_load_dwordx4 v[12:15], v114, s[0:1] offset:3072 nt
	s_add_i32 s37, s36, s14
	s_cmpk_lt_i32 s37, 0x4100
	s_cselect_b32 s37, s37, s36
	s_cmpk_gt_i32 s37, 0x207f
	s_cselect_b32 s43, 0x2080, 0
	s_cselect_b32 vcc_lo, 0x2000, 0
	s_cselect_b32 vcc_hi, 0x80, 0
	s_sub_i32 s43, s37, s43
	s_add_i32 vcc_lo, vcc_lo, s43
	s_addk_i32 vcc_lo, 0xff80
	s_add_i32 vcc_hi, vcc_hi, s43
	s_cmpk_lt_i32 s43, 0x80
	s_cselect_b32 vcc_lo, vcc_hi, vcc_lo
	s_cselect_b32 s12, s40, s92
	s_cselect_b32 s13, s41, s93
	s_lshl_b32 vcc_lo, vcc_lo, 12
	s_lshl_b32 vcc_hi, s37, 11
	v_add_u32_e32 v115, vcc_lo, v106
	v_add_u32_e32 v118, vcc_hi, v107
	global_load_dwordx2 v[40:41], v118, s[4:5] nt
	global_load_dwordx2 v[42:43], v118, s[4:5] offset:512 nt
	global_load_dwordx2 v[44:45], v118, s[4:5] offset:1024 nt
	global_load_dwordx2 v[46:47], v118, s[4:5] offset:1536 nt
	global_load_dwordx4 v[24:27], v115, s[12:13] nt
	global_load_dwordx4 v[28:31], v115, s[12:13] offset:1024 nt
	global_load_dwordx4 v[32:35], v115, s[12:13] offset:2048 nt
	global_load_dwordx4 v[36:39], v115, s[12:13] offset:3072 nt
	s_lshl_b32 s37, s14, 1
	s_add_i32 s37, s36, s37
	s_cmpk_lt_i32 s37, 0x4100
	s_cselect_b32 s37, s37, s36
	s_cmpk_gt_i32 s37, 0x207f
	s_cselect_b32 s43, 0x2080, 0
	s_cselect_b32 vcc_lo, 0x2000, 0
	s_cselect_b32 vcc_hi, 0x80, 0
	s_sub_i32 s43, s37, s43
	s_add_i32 vcc_lo, vcc_lo, s43
	s_addk_i32 vcc_lo, 0xff80
	s_add_i32 vcc_hi, vcc_hi, s43
	s_cmpk_lt_i32 s43, 0x80
	s_cselect_b32 vcc_lo, vcc_hi, vcc_lo
	s_cselect_b32 s38, s40, s92
	s_cselect_b32 s39, s41, s93
	s_lshl_b32 vcc_lo, vcc_lo, 12
	s_lshl_b32 vcc_hi, s37, 11
	v_add_u32_e32 v116, vcc_lo, v106
	v_add_u32_e32 v119, vcc_hi, v107
	global_load_dwordx2 v[64:65], v119, s[4:5] nt
	global_load_dwordx2 v[66:67], v119, s[4:5] offset:512 nt
	global_load_dwordx2 v[68:69], v119, s[4:5] offset:1024 nt
	global_load_dwordx2 v[70:71], v119, s[4:5] offset:1536 nt
	global_load_dwordx4 v[48:51], v116, s[38:39] nt
	global_load_dwordx4 v[52:55], v116, s[38:39] offset:1024 nt
	global_load_dwordx4 v[56:59], v116, s[38:39] offset:2048 nt
	global_load_dwordx4 v[60:63], v116, s[38:39] offset:3072 nt
	s_waitcnt vmcnt(16)
	v_lshlrev_b32_e32 v120, 16, v16
	v_and_b32_e32 v16, 0xffff0000, v16
	v_lshlrev_b32_e32 v121, 16, v17
	v_and_b32_e32 v17, 0xffff0000, v17
	v_lshlrev_b32_e32 v122, 16, v18
	v_and_b32_e32 v18, 0xffff0000, v18
	v_lshlrev_b32_e32 v123, 16, v19
	v_and_b32_e32 v19, 0xffff0000, v19
	v_lshlrev_b32_e32 v124, 16, v20
	v_and_b32_e32 v20, 0xffff0000, v20
	v_lshlrev_b32_e32 v125, 16, v21
	v_and_b32_e32 v21, 0xffff0000, v21
	v_lshlrev_b32_e32 v126, 16, v22
	v_and_b32_e32 v22, 0xffff0000, v22
	v_lshlrev_b32_e32 v127, 16, v23
	v_and_b32_e32 v23, 0xffff0000, v23
	v_mul_f32_e32 v128, v16, v16
	v_mul_f32_e32 v129, v18, v18
	v_mul_f32_e32 v130, v20, v20
	v_mul_f32_e32 v131, v22, v22
	v_fmac_f32_e32 v128, v120, v120
	v_fmac_f32_e32 v129, v122, v122
	v_fmac_f32_e32 v130, v124, v124
	v_fmac_f32_e32 v131, v126, v126
	v_fmac_f32_e32 v128, v121, v121
	v_fmac_f32_e32 v129, v123, v123
	v_fmac_f32_e32 v130, v125, v125
	v_fmac_f32_e32 v131, v127, v127
	v_fmac_f32_e32 v128, v17, v17
	v_fmac_f32_e32 v129, v19, v19
	v_fmac_f32_e32 v130, v21, v21
	v_fmac_f32_e32 v131, v23, v23
	v_add_f32_e32 v132, v128, v129
	v_add_f32_e32 v132, v132, v130
	v_add_f32_e32 v132, v132, v131
	ds_bpermute_b32 v138, v108, v132
	s_waitcnt lgkmcnt(0)
	v_add_f32_e32 v132, v132, v138
	ds_bpermute_b32 v138, v109, v132
	s_waitcnt lgkmcnt(0)
	v_add_f32_e32 v132, v132, v138
	ds_bpermute_b32 v138, v110, v132
	s_waitcnt lgkmcnt(0)
	v_add_f32_e32 v132, v132, v138
	ds_bpermute_b32 v138, v111, v132
	s_waitcnt lgkmcnt(0)
	v_add_f32_e32 v132, v132, v138
	ds_bpermute_b32 v138, v112, v132
	s_waitcnt lgkmcnt(0)
	v_add_f32_e32 v132, v132, v138
	ds_bpermute_b32 v138, v113, v132
	s_waitcnt lgkmcnt(0)
	v_add_f32_e32 v132, v132, v138
	v_fmamk_f32 v132, v132, 0x3a800000, v177
	v_mov_b32_e32 v135, 0x800000
	v_cmp_gt_f32_e32 vcc, v135, v132
	v_mul_f32_e32 v133, 0x4b800000, v132
	s_nop 1
	v_cndmask_b32_e32 v132, v132, v133, vcc
	v_rsq_f32_e32 v132, v132
	s_nop 0
	v_mul_f32_e32 v133, 0x45800000, v132
	v_cndmask_b32_e32 v134, v132, v133, vcc
	v_mul_f32_e32 v120, v72, v120
	v_mul_f32_e32 v16, v73, v16
	v_mul_f32_e32 v121, v74, v121
	v_mul_f32_e32 v17, v75, v17
	v_mul_f32_e32 v122, v76, v122
	v_mul_f32_e32 v18, v77, v18
	v_mul_f32_e32 v123, v78, v123
	v_mul_f32_e32 v19, v79, v19
	v_mul_f32_e32 v124, v80, v124
	v_mul_f32_e32 v20, v81, v20
	v_mul_f32_e32 v125, v82, v125
	v_mul_f32_e32 v21, v83, v21
	v_mul_f32_e32 v126, v84, v126
	v_mul_f32_e32 v22, v85, v22
	v_mul_f32_e32 v127, v86, v127
	v_mul_f32_e32 v23, v87, v23
	v_fmac_f32_e32 v0, v120, v134
	v_fmac_f32_e32 v1, v16, v134
	v_fmac_f32_e32 v2, v121, v134
	v_fmac_f32_e32 v3, v17, v134
	v_fmac_f32_e32 v4, v122, v134
	v_fmac_f32_e32 v5, v18, v134
	v_fmac_f32_e32 v6, v123, v134
	v_fmac_f32_e32 v7, v19, v134
	v_fmac_f32_e32 v8, v124, v134
	v_fmac_f32_e32 v9, v20, v134
	v_fmac_f32_e32 v10, v125, v134
	v_fmac_f32_e32 v11, v21, v134
	v_fmac_f32_e32 v12, v126, v134
	v_fmac_f32_e32 v13, v22, v134
	v_fmac_f32_e32 v14, v127, v134
	v_fmac_f32_e32 v15, v23, v134
	global_store_dwordx4 v114, v[0:3], s[0:1] nt
	global_store_dwordx4 v114, v[4:7], s[0:1] offset:1024 nt
	global_store_dwordx4 v114, v[8:11], s[0:1] offset:2048 nt
	global_store_dwordx4 v114, v[12:15], s[0:1] offset:3072 nt
	s_cmp_eq_u32 s42, 0
	s_cbranch_scc1 .LnrmA_nopre0
	v_mul_f32_e32 v128, v1, v1
	v_mul_f32_e32 v129, v5, v5
	v_mul_f32_e32 v130, v9, v9
	v_mul_f32_e32 v131, v13, v13
	v_fmac_f32_e32 v128, v0, v0
	v_fmac_f32_e32 v129, v4, v4
	v_fmac_f32_e32 v130, v8, v8
	v_fmac_f32_e32 v131, v12, v12
	v_fmac_f32_e32 v128, v2, v2
	v_fmac_f32_e32 v129, v6, v6
	v_fmac_f32_e32 v130, v10, v10
	v_fmac_f32_e32 v131, v14, v14
	v_fmac_f32_e32 v128, v3, v3
	v_fmac_f32_e32 v129, v7, v7
	v_fmac_f32_e32 v130, v11, v11
	v_fmac_f32_e32 v131, v15, v15
	v_add_f32_e32 v132, v128, v129
	v_add_f32_e32 v132, v130, v132
	v_add_f32_e32 v132, v131, v132
	ds_bpermute_b32 v138, v108, v132
	s_waitcnt lgkmcnt(0)
	v_add_f32_e32 v132, v132, v138
	ds_bpermute_b32 v138, v109, v132
	s_waitcnt lgkmcnt(0)
	v_add_f32_e32 v132, v132, v138
	ds_bpermute_b32 v138, v110, v132
	s_waitcnt lgkmcnt(0)
	v_add_f32_e32 v132, v132, v138
	ds_bpermute_b32 v138, v111, v132
	s_waitcnt lgkmcnt(0)
	v_add_f32_e32 v132, v132, v138
	ds_bpermute_b32 v138, v112, v132
	s_waitcnt lgkmcnt(0)
	v_add_f32_e32 v132, v132, v138
	ds_bpermute_b32 v138, v113, v132
	s_waitcnt lgkmcnt(0)
	v_add_f32_e32 v132, v132, v138
	v_fmamk_f32 v132, v132, 0x3a800000, v177
	v_mov_b32_e32 v135, 0x800000
	v_cmp_gt_f32_e32 vcc, v135, v132
	v_mul_f32_e32 v133, 0x4b800000, v132
	s_nop 1
	v_cndmask_b32_e32 v132, v132, v133, vcc
	v_rsq_f32_e32 v132, v132
	s_nop 0
	v_mul_f32_e32 v133, 0x45800000, v132
	v_cndmask_b32_e32 v134, v132, v133, vcc
	v_mul_f32_e32 v0, v0, v88
	v_mul_f32_e32 v1, v1, v89
	v_mul_f32_e32 v2, v2, v90
	v_mul_f32_e32 v3, v3, v91
	v_mul_f32_e32 v4, v4, v92
	v_mul_f32_e32 v5, v5, v93
	v_mul_f32_e32 v6, v6, v94
	v_mul_f32_e32 v7, v7, v95
	v_mul_f32_e32 v8, v8, v96
	v_mul_f32_e32 v9, v9, v97
	v_mul_f32_e32 v10, v10, v98
	v_mul_f32_e32 v11, v11, v99
	v_mul_f32_e32 v12, v12, v100
	v_mul_f32_e32 v13, v13, v101
	v_mul_f32_e32 v14, v14, v102
	v_mul_f32_e32 v15, v15, v103
	v_mul_f32_e32 v0, v0, v134
	v_mul_f32_e32 v1, v1, v134
	v_mul_f32_e32 v2, v2, v134
	v_mul_f32_e32 v3, v3, v134
	v_mul_f32_e32 v4, v4, v134
	v_mul_f32_e32 v5, v5, v134
	v_mul_f32_e32 v6, v6, v134
	v_mul_f32_e32 v7, v7, v134
	v_mul_f32_e32 v8, v8, v134
	v_mul_f32_e32 v9, v9, v134
	v_mul_f32_e32 v10, v10, v134
	v_mul_f32_e32 v11, v11, v134
	v_mul_f32_e32 v12, v12, v134
	v_mul_f32_e32 v13, v13, v134
	v_mul_f32_e32 v14, v14, v134
	v_mul_f32_e32 v15, v15, v134
	v_cvt_pk_bf16_f32 v120, v0, v1
	v_cvt_pk_bf16_f32 v121, v2, v3
	v_cvt_pk_bf16_f32 v122, v4, v5
	v_cvt_pk_bf16_f32 v123, v6, v7
	v_cvt_pk_bf16_f32 v124, v8, v9
	v_cvt_pk_bf16_f32 v125, v10, v11
	v_cvt_pk_bf16_f32 v126, v12, v13
	v_cvt_pk_bf16_f32 v127, v14, v15
	global_store_dwordx2 v117, v[120:121], s[4:5] nt
	global_store_dwordx2 v117, v[122:123], s[4:5] offset:512 nt
	global_store_dwordx2 v117, v[124:125], s[4:5] offset:1024 nt
	global_store_dwordx2 v117, v[126:127], s[4:5] offset:1536 nt
.LnrmA_nopre0:
	s_add_i32 s37, s36, s14
	s_cmpk_lt_i32 s37, 0x4100
	s_cbranch_scc0 .LnrmA_skip1
	s_waitcnt vmcnt(12)
	v_lshlrev_b32_e32 v120, 16, v40
	v_and_b32_e32 v40, 0xffff0000, v40
	v_lshlrev_b32_e32 v121, 16, v41
	v_and_b32_e32 v41, 0xffff0000, v41
	v_lshlrev_b32_e32 v122, 16, v42
	v_and_b32_e32 v42, 0xffff0000, v42
	v_lshlrev_b32_e32 v123, 16, v43
	v_and_b32_e32 v43, 0xffff0000, v43
	v_lshlrev_b32_e32 v124, 16, v44
	v_and_b32_e32 v44, 0xffff0000, v44
	v_lshlrev_b32_e32 v125, 16, v45
	v_and_b32_e32 v45, 0xffff0000, v45
	v_lshlrev_b32_e32 v126, 16, v46
	v_and_b32_e32 v46, 0xffff0000, v46
	v_lshlrev_b32_e32 v127, 16, v47
	v_and_b32_e32 v47, 0xffff0000, v47
	v_mul_f32_e32 v128, v40, v40
	v_mul_f32_e32 v129, v42, v42
	v_mul_f32_e32 v130, v44, v44
	v_mul_f32_e32 v131, v46, v46
	v_fmac_f32_e32 v128, v120, v120
	v_fmac_f32_e32 v129, v122, v122
	v_fmac_f32_e32 v130, v124, v124
	v_fmac_f32_e32 v131, v126, v126
	v_fmac_f32_e32 v128, v121, v121
	v_fmac_f32_e32 v129, v123, v123
	v_fmac_f32_e32 v130, v125, v125
	v_fmac_f32_e32 v131, v127, v127
	v_fmac_f32_e32 v128, v41, v41
	v_fmac_f32_e32 v129, v43, v43
	v_fmac_f32_e32 v130, v45, v45
	v_fmac_f32_e32 v131, v47, v47
	v_add_f32_e32 v132, v128, v129
	v_add_f32_e32 v132, v132, v130
	v_add_f32_e32 v132, v132, v131
	ds_bpermute_b32 v138, v108, v132
	s_waitcnt lgkmcnt(0)
	v_add_f32_e32 v132, v132, v138
	ds_bpermute_b32 v138, v109, v132
	s_waitcnt lgkmcnt(0)
	v_add_f32_e32 v132, v132, v138
	ds_bpermute_b32 v138, v110, v132
	s_waitcnt lgkmcnt(0)
	v_add_f32_e32 v132, v132, v138
	ds_bpermute_b32 v138, v111, v132
	s_waitcnt lgkmcnt(0)
	v_add_f32_e32 v132, v132, v138
	ds_bpermute_b32 v138, v112, v132
	s_waitcnt lgkmcnt(0)
	v_add_f32_e32 v132, v132, v138
	ds_bpermute_b32 v138, v113, v132
	s_waitcnt lgkmcnt(0)
	v_add_f32_e32 v132, v132, v138
	v_fmamk_f32 v132, v132, 0x3a800000, v177
	v_mov_b32_e32 v135, 0x800000
	v_cmp_gt_f32_e32 vcc, v135, v132
	v_mul_f32_e32 v133, 0x4b800000, v132
	s_nop 1
	v_cndmask_b32_e32 v132, v132, v133, vcc
	v_rsq_f32_e32 v132, v132
	s_nop 0
	v_mul_f32_e32 v133, 0x45800000, v132
	v_cndmask_b32_e32 v134, v132, v133, vcc
	v_mul_f32_e32 v120, v72, v120
	v_mul_f32_e32 v40, v73, v40
	v_mul_f32_e32 v121, v74, v121
	v_mul_f32_e32 v41, v75, v41
	v_mul_f32_e32 v122, v76, v122
	v_mul_f32_e32 v42, v77, v42
	v_mul_f32_e32 v123, v78, v123
	v_mul_f32_e32 v43, v79, v43
	v_mul_f32_e32 v124, v80, v124
	v_mul_f32_e32 v44, v81, v44
	v_mul_f32_e32 v125, v82, v125
	v_mul_f32_e32 v45, v83, v45
	v_mul_f32_e32 v126, v84, v126
	v_mul_f32_e32 v46, v85, v46
	v_mul_f32_e32 v127, v86, v127
	v_mul_f32_e32 v47, v87, v47
	v_fmac_f32_e32 v24, v120, v134
	v_fmac_f32_e32 v25, v40, v134
	v_fmac_f32_e32 v26, v121, v134
	v_fmac_f32_e32 v27, v41, v134
	v_fmac_f32_e32 v28, v122, v134
	v_fmac_f32_e32 v29, v42, v134
	v_fmac_f32_e32 v30, v123, v134
	v_fmac_f32_e32 v31, v43, v134
	v_fmac_f32_e32 v32, v124, v134
	v_fmac_f32_e32 v33, v44, v134
	v_fmac_f32_e32 v34, v125, v134
	v_fmac_f32_e32 v35, v45, v134
	v_fmac_f32_e32 v36, v126, v134
	v_fmac_f32_e32 v37, v46, v134
	v_fmac_f32_e32 v38, v127, v134
	v_fmac_f32_e32 v39, v47, v134
	global_store_dwordx4 v115, v[24:27], s[12:13] nt
	global_store_dwordx4 v115, v[28:31], s[12:13] offset:1024 nt
	global_store_dwordx4 v115, v[32:35], s[12:13] offset:2048 nt
	global_store_dwordx4 v115, v[36:39], s[12:13] offset:3072 nt
	s_cmp_eq_u32 s42, 0
	s_cbranch_scc1 .LnrmA_skip1
	v_mul_f32_e32 v128, v25, v25
	v_mul_f32_e32 v129, v29, v29
	v_mul_f32_e32 v130, v33, v33
	v_mul_f32_e32 v131, v37, v37
	v_fmac_f32_e32 v128, v24, v24
	v_fmac_f32_e32 v129, v28, v28
	v_fmac_f32_e32 v130, v32, v32
	v_fmac_f32_e32 v131, v36, v36
	v_fmac_f32_e32 v128, v26, v26
	v_fmac_f32_e32 v129, v30, v30
	v_fmac_f32_e32 v130, v34, v34
	v_fmac_f32_e32 v131, v38, v38
	v_fmac_f32_e32 v128, v27, v27
	v_fmac_f32_e32 v129, v31, v31
	v_fmac_f32_e32 v130, v35, v35
	v_fmac_f32_e32 v131, v39, v39
	v_add_f32_e32 v132, v128, v129
	v_add_f32_e32 v132, v130, v132
	v_add_f32_e32 v132, v131, v132
	ds_bpermute_b32 v138, v108, v132
	s_waitcnt lgkmcnt(0)
	v_add_f32_e32 v132, v132, v138
	ds_bpermute_b32 v138, v109, v132
	s_waitcnt lgkmcnt(0)
	v_add_f32_e32 v132, v132, v138
	ds_bpermute_b32 v138, v110, v132
	s_waitcnt lgkmcnt(0)
	v_add_f32_e32 v132, v132, v138
	ds_bpermute_b32 v138, v111, v132
	s_waitcnt lgkmcnt(0)
	v_add_f32_e32 v132, v132, v138
	ds_bpermute_b32 v138, v112, v132
	s_waitcnt lgkmcnt(0)
	v_add_f32_e32 v132, v132, v138
	ds_bpermute_b32 v138, v113, v132
	s_waitcnt lgkmcnt(0)
	v_add_f32_e32 v132, v132, v138
	v_fmamk_f32 v132, v132, 0x3a800000, v177
	v_mov_b32_e32 v135, 0x800000
	v_cmp_gt_f32_e32 vcc, v135, v132
	v_mul_f32_e32 v133, 0x4b800000, v132
	s_nop 1
	v_cndmask_b32_e32 v132, v132, v133, vcc
	v_rsq_f32_e32 v132, v132
	s_nop 0
	v_mul_f32_e32 v133, 0x45800000, v132
	v_cndmask_b32_e32 v134, v132, v133, vcc
	v_mul_f32_e32 v24, v24, v88
	v_mul_f32_e32 v25, v25, v89
	v_mul_f32_e32 v26, v26, v90
	v_mul_f32_e32 v27, v27, v91
	v_mul_f32_e32 v28, v28, v92
	v_mul_f32_e32 v29, v29, v93
	v_mul_f32_e32 v30, v30, v94
	v_mul_f32_e32 v31, v31, v95
	v_mul_f32_e32 v32, v32, v96
	v_mul_f32_e32 v33, v33, v97
	v_mul_f32_e32 v34, v34, v98
	v_mul_f32_e32 v35, v35, v99
	v_mul_f32_e32 v36, v36, v100
	v_mul_f32_e32 v37, v37, v101
	v_mul_f32_e32 v38, v38, v102
	v_mul_f32_e32 v39, v39, v103
	v_mul_f32_e32 v24, v24, v134
	v_mul_f32_e32 v25, v25, v134
	v_mul_f32_e32 v26, v26, v134
	v_mul_f32_e32 v27, v27, v134
	v_mul_f32_e32 v28, v28, v134
	v_mul_f32_e32 v29, v29, v134
	v_mul_f32_e32 v30, v30, v134
	v_mul_f32_e32 v31, v31, v134
	v_mul_f32_e32 v32, v32, v134
	v_mul_f32_e32 v33, v33, v134
	v_mul_f32_e32 v34, v34, v134
	v_mul_f32_e32 v35, v35, v134
	v_mul_f32_e32 v36, v36, v134
	v_mul_f32_e32 v37, v37, v134
	v_mul_f32_e32 v38, v38, v134
	v_mul_f32_e32 v39, v39, v134
	v_cvt_pk_bf16_f32 v120, v24, v25
	v_cvt_pk_bf16_f32 v121, v26, v27
	v_cvt_pk_bf16_f32 v122, v28, v29
	v_cvt_pk_bf16_f32 v123, v30, v31
	v_cvt_pk_bf16_f32 v124, v32, v33
	v_cvt_pk_bf16_f32 v125, v34, v35
	v_cvt_pk_bf16_f32 v126, v36, v37
	v_cvt_pk_bf16_f32 v127, v38, v39
	global_store_dwordx2 v118, v[120:121], s[4:5] nt
	global_store_dwordx2 v118, v[122:123], s[4:5] offset:512 nt
	global_store_dwordx2 v118, v[124:125], s[4:5] offset:1024 nt
	global_store_dwordx2 v118, v[126:127], s[4:5] offset:1536 nt
.LnrmA_skip1:
	s_lshl_b32 s37, s14, 1
	s_add_i32 s37, s36, s37
	s_cmpk_lt_i32 s37, 0x4100
	s_cbranch_scc0 .LnrmA_skip2
	s_waitcnt vmcnt(8)
	v_lshlrev_b32_e32 v120, 16, v64
	v_and_b32_e32 v64, 0xffff0000, v64
	v_lshlrev_b32_e32 v121, 16, v65
	v_and_b32_e32 v65, 0xffff0000, v65
	v_lshlrev_b32_e32 v122, 16, v66
	v_and_b32_e32 v66, 0xffff0000, v66
	v_lshlrev_b32_e32 v123, 16, v67
	v_and_b32_e32 v67, 0xffff0000, v67
	v_lshlrev_b32_e32 v124, 16, v68
	v_and_b32_e32 v68, 0xffff0000, v68
	v_lshlrev_b32_e32 v125, 16, v69
	v_and_b32_e32 v69, 0xffff0000, v69
	v_lshlrev_b32_e32 v126, 16, v70
	v_and_b32_e32 v70, 0xffff0000, v70
	v_lshlrev_b32_e32 v127, 16, v71
	v_and_b32_e32 v71, 0xffff0000, v71
	v_mul_f32_e32 v128, v64, v64
	v_mul_f32_e32 v129, v66, v66
	v_mul_f32_e32 v130, v68, v68
	v_mul_f32_e32 v131, v70, v70
	v_fmac_f32_e32 v128, v120, v120
	v_fmac_f32_e32 v129, v122, v122
	v_fmac_f32_e32 v130, v124, v124
	v_fmac_f32_e32 v131, v126, v126
	v_fmac_f32_e32 v128, v121, v121
	v_fmac_f32_e32 v129, v123, v123
	v_fmac_f32_e32 v130, v125, v125
	v_fmac_f32_e32 v131, v127, v127
	v_fmac_f32_e32 v128, v65, v65
	v_fmac_f32_e32 v129, v67, v67
	v_fmac_f32_e32 v130, v69, v69
	v_fmac_f32_e32 v131, v71, v71
	v_add_f32_e32 v132, v128, v129
	v_add_f32_e32 v132, v132, v130
	v_add_f32_e32 v132, v132, v131
	ds_bpermute_b32 v138, v108, v132
	s_waitcnt lgkmcnt(0)
	v_add_f32_e32 v132, v132, v138
	ds_bpermute_b32 v138, v109, v132
	s_waitcnt lgkmcnt(0)
	v_add_f32_e32 v132, v132, v138
	ds_bpermute_b32 v138, v110, v132
	s_waitcnt lgkmcnt(0)
	v_add_f32_e32 v132, v132, v138
	ds_bpermute_b32 v138, v111, v132
	s_waitcnt lgkmcnt(0)
	v_add_f32_e32 v132, v132, v138
	ds_bpermute_b32 v138, v112, v132
	s_waitcnt lgkmcnt(0)
	v_add_f32_e32 v132, v132, v138
	ds_bpermute_b32 v138, v113, v132
	s_waitcnt lgkmcnt(0)
	v_add_f32_e32 v132, v132, v138
	v_fmamk_f32 v132, v132, 0x3a800000, v177
	v_mov_b32_e32 v135, 0x800000
	v_cmp_gt_f32_e32 vcc, v135, v132
	v_mul_f32_e32 v133, 0x4b800000, v132
	s_nop 1
	v_cndmask_b32_e32 v132, v132, v133, vcc
	v_rsq_f32_e32 v132, v132
	s_nop 0
	v_mul_f32_e32 v133, 0x45800000, v132
	v_cndmask_b32_e32 v134, v132, v133, vcc
	v_mul_f32_e32 v120, v72, v120
	v_mul_f32_e32 v64, v73, v64
	v_mul_f32_e32 v121, v74, v121
	v_mul_f32_e32 v65, v75, v65
	v_mul_f32_e32 v122, v76, v122
	v_mul_f32_e32 v66, v77, v66
	v_mul_f32_e32 v123, v78, v123
	v_mul_f32_e32 v67, v79, v67
	v_mul_f32_e32 v124, v80, v124
	v_mul_f32_e32 v68, v81, v68
	v_mul_f32_e32 v125, v82, v125
	v_mul_f32_e32 v69, v83, v69
	v_mul_f32_e32 v126, v84, v126
	v_mul_f32_e32 v70, v85, v70
	v_mul_f32_e32 v127, v86, v127
	v_mul_f32_e32 v71, v87, v71
	v_fmac_f32_e32 v48, v120, v134
	v_fmac_f32_e32 v49, v64, v134
	v_fmac_f32_e32 v50, v121, v134
	v_fmac_f32_e32 v51, v65, v134
	v_fmac_f32_e32 v52, v122, v134
	v_fmac_f32_e32 v53, v66, v134
	v_fmac_f32_e32 v54, v123, v134
	v_fmac_f32_e32 v55, v67, v134
	v_fmac_f32_e32 v56, v124, v134
	v_fmac_f32_e32 v57, v68, v134
	v_fmac_f32_e32 v58, v125, v134
	v_fmac_f32_e32 v59, v69, v134
	v_fmac_f32_e32 v60, v126, v134
	v_fmac_f32_e32 v61, v70, v134
	v_fmac_f32_e32 v62, v127, v134
	v_fmac_f32_e32 v63, v71, v134
	global_store_dwordx4 v116, v[48:51], s[38:39] nt
	global_store_dwordx4 v116, v[52:55], s[38:39] offset:1024 nt
	global_store_dwordx4 v116, v[56:59], s[38:39] offset:2048 nt
	global_store_dwordx4 v116, v[60:63], s[38:39] offset:3072 nt
	s_cmp_eq_u32 s42, 0
	s_cbranch_scc1 .LnrmA_skip2
	v_mul_f32_e32 v128, v49, v49
	v_mul_f32_e32 v129, v53, v53
	v_mul_f32_e32 v130, v57, v57
	v_mul_f32_e32 v131, v61, v61
	v_fmac_f32_e32 v128, v48, v48
	v_fmac_f32_e32 v129, v52, v52
	v_fmac_f32_e32 v130, v56, v56
	v_fmac_f32_e32 v131, v60, v60
	v_fmac_f32_e32 v128, v50, v50
	v_fmac_f32_e32 v129, v54, v54
	v_fmac_f32_e32 v130, v58, v58
	v_fmac_f32_e32 v131, v62, v62
	v_fmac_f32_e32 v128, v51, v51
	v_fmac_f32_e32 v129, v55, v55
	v_fmac_f32_e32 v130, v59, v59
	v_fmac_f32_e32 v131, v63, v63
	v_add_f32_e32 v132, v128, v129
	v_add_f32_e32 v132, v130, v132
	v_add_f32_e32 v132, v131, v132
	ds_bpermute_b32 v138, v108, v132
	s_waitcnt lgkmcnt(0)
	v_add_f32_e32 v132, v132, v138
	ds_bpermute_b32 v138, v109, v132
	s_waitcnt lgkmcnt(0)
	v_add_f32_e32 v132, v132, v138
	ds_bpermute_b32 v138, v110, v132
	s_waitcnt lgkmcnt(0)
	v_add_f32_e32 v132, v132, v138
	ds_bpermute_b32 v138, v111, v132
	s_waitcnt lgkmcnt(0)
	v_add_f32_e32 v132, v132, v138
	ds_bpermute_b32 v138, v112, v132
	s_waitcnt lgkmcnt(0)
	v_add_f32_e32 v132, v132, v138
	ds_bpermute_b32 v138, v113, v132
	s_waitcnt lgkmcnt(0)
	v_add_f32_e32 v132, v132, v138
	v_fmamk_f32 v132, v132, 0x3a800000, v177
	v_mov_b32_e32 v135, 0x800000
	v_cmp_gt_f32_e32 vcc, v135, v132
	v_mul_f32_e32 v133, 0x4b800000, v132
	s_nop 1
	v_cndmask_b32_e32 v132, v132, v133, vcc
	v_rsq_f32_e32 v132, v132
	s_nop 0
	v_mul_f32_e32 v133, 0x45800000, v132
	v_cndmask_b32_e32 v134, v132, v133, vcc
	v_mul_f32_e32 v48, v48, v88
	v_mul_f32_e32 v49, v49, v89
	v_mul_f32_e32 v50, v50, v90
	v_mul_f32_e32 v51, v51, v91
	v_mul_f32_e32 v52, v52, v92
	v_mul_f32_e32 v53, v53, v93
	v_mul_f32_e32 v54, v54, v94
	v_mul_f32_e32 v55, v55, v95
	v_mul_f32_e32 v56, v56, v96
	v_mul_f32_e32 v57, v57, v97
	v_mul_f32_e32 v58, v58, v98
	v_mul_f32_e32 v59, v59, v99
	v_mul_f32_e32 v60, v60, v100
	v_mul_f32_e32 v61, v61, v101
	v_mul_f32_e32 v62, v62, v102
	v_mul_f32_e32 v63, v63, v103
	v_mul_f32_e32 v48, v48, v134
	v_mul_f32_e32 v49, v49, v134
	v_mul_f32_e32 v50, v50, v134
	v_mul_f32_e32 v51, v51, v134
	v_mul_f32_e32 v52, v52, v134
	v_mul_f32_e32 v53, v53, v134
	v_mul_f32_e32 v54, v54, v134
	v_mul_f32_e32 v55, v55, v134
	v_mul_f32_e32 v56, v56, v134
	v_mul_f32_e32 v57, v57, v134
	v_mul_f32_e32 v58, v58, v134
	v_mul_f32_e32 v59, v59, v134
	v_mul_f32_e32 v60, v60, v134
	v_mul_f32_e32 v61, v61, v134
	v_mul_f32_e32 v62, v62, v134
	v_mul_f32_e32 v63, v63, v134
	v_cvt_pk_bf16_f32 v120, v48, v49
	v_cvt_pk_bf16_f32 v121, v50, v51
	v_cvt_pk_bf16_f32 v122, v52, v53
	v_cvt_pk_bf16_f32 v123, v54, v55
	v_cvt_pk_bf16_f32 v124, v56, v57
	v_cvt_pk_bf16_f32 v125, v58, v59
	v_cvt_pk_bf16_f32 v126, v60, v61
	v_cvt_pk_bf16_f32 v127, v62, v63
	global_store_dwordx2 v119, v[120:121], s[4:5] nt
	global_store_dwordx2 v119, v[122:123], s[4:5] offset:512 nt
	global_store_dwordx2 v119, v[124:125], s[4:5] offset:1024 nt
	global_store_dwordx2 v119, v[126:127], s[4:5] offset:1536 nt
.LnrmA_skip2:
	s_mul_i32 s37, s14, 3
	s_add_i32 s36, s36, s37
	s_cmpk_lt_i32 s36, 0x4100
	s_cbranch_scc1 .LnrmA_loop

.LBB0_1342:
	s_cmp_lg_u32 s96, 0x100
	s_cbranch_scc1 .Lic1_no
	s_cmp_lt_u32 s2, 150
	s_cbranch_scc1 .Lic1_no
	v_writelane_b32 v253, s0, 0
	v_writelane_b32 v253, s1, 1
	v_writelane_b32 v253, s2, 2
	v_writelane_b32 v253, s3, 3
	v_writelane_b32 v253, s4, 4
	v_writelane_b32 v253, s5, 5
	v_writelane_b32 v253, s6, 6
	v_writelane_b32 v253, s7, 7
	v_writelane_b32 v253, s8, 8
	v_writelane_b32 v253, s9, 9
	v_writelane_b32 v253, s10, 10
	v_writelane_b32 v253, s11, 11
	v_writelane_b32 v253, s12, 12
	v_writelane_b32 v253, s13, 13
	v_writelane_b32 v253, s14, 14
	v_writelane_b32 v253, s15, 15
	v_writelane_b32 v253, s16, 16
	v_writelane_b32 v253, s17, 17
	v_writelane_b32 v253, s18, 18
	v_writelane_b32 v253, s19, 19
	v_writelane_b32 v253, s20, 20
	v_writelane_b32 v253, s21, 21
	v_writelane_b32 v253, s22, 22
	v_writelane_b32 v253, s23, 23
	v_writelane_b32 v253, s24, 24
	v_writelane_b32 v253, s25, 25
	v_writelane_b32 v253, s26, 26
	v_writelane_b32 v253, s27, 27
	v_writelane_b32 v253, s28, 28
	v_writelane_b32 v253, s29, 29
	v_writelane_b32 v253, s30, 30
	v_writelane_b32 v253, s31, 31
	v_writelane_b32 v253, s32, 32
	v_writelane_b32 v253, s33, 33
	v_writelane_b32 v253, s34, 34
	v_writelane_b32 v253, s35, 35
	v_writelane_b32 v253, s36, 36
	v_writelane_b32 v253, s37, 37
	v_writelane_b32 v253, s38, 38
	v_writelane_b32 v253, s39, 39
	v_writelane_b32 v253, s40, 40
	v_writelane_b32 v253, s41, 41
	v_writelane_b32 v253, s42, 42
	v_writelane_b32 v253, s43, 43
	v_writelane_b32 v253, s44, 44
	v_writelane_b32 v253, s45, 45
	v_writelane_b32 v253, s46, 46
	v_writelane_b32 v253, s47, 47
	v_writelane_b32 v253, s48, 48
	v_writelane_b32 v253, s49, 49
	v_writelane_b32 v253, s50, 50
	v_writelane_b32 v253, s51, 51
	v_writelane_b32 v253, s52, 52
	v_writelane_b32 v253, s53, 53
	v_writelane_b32 v253, s54, 54
	v_writelane_b32 v253, s55, 55
	v_writelane_b32 v253, s56, 56
	v_writelane_b32 v253, s57, 57
	v_writelane_b32 v253, s58, 58
	v_writelane_b32 v253, s59, 59
	v_writelane_b32 v253, s60, 60
	v_writelane_b32 v253, s61, 61
	v_writelane_b32 v253, s62, 62
	v_writelane_b32 v253, s63, 63
	v_writelane_b32 v254, s64, 0
	v_writelane_b32 v254, s65, 1
	v_writelane_b32 v254, s66, 2
	v_writelane_b32 v254, s67, 3
	v_writelane_b32 v254, s68, 4
	v_writelane_b32 v254, s69, 5
	v_writelane_b32 v254, s70, 6
	v_writelane_b32 v254, s71, 7
	v_writelane_b32 v254, s72, 8
	v_writelane_b32 v254, s73, 9
	v_writelane_b32 v254, s74, 10
	v_writelane_b32 v254, s75, 11
	v_writelane_b32 v254, s76, 12
	v_writelane_b32 v254, s77, 13
	v_writelane_b32 v254, s78, 14
	v_writelane_b32 v254, s79, 15
	v_writelane_b32 v254, s80, 16
	v_writelane_b32 v254, s81, 17
	v_writelane_b32 v254, s82, 18
	v_writelane_b32 v254, s83, 19
	v_writelane_b32 v254, s84, 20
	v_writelane_b32 v254, s85, 21
	v_writelane_b32 v254, s86, 22
	v_writelane_b32 v254, s87, 23
	v_writelane_b32 v254, s88, 24
	v_writelane_b32 v254, s89, 25
	v_writelane_b32 v254, s90, 26
	v_writelane_b32 v254, s91, 27
	v_writelane_b32 v254, s92, 28
	v_writelane_b32 v254, s93, 29
	v_writelane_b32 v254, s94, 30
	v_writelane_b32 v254, s95, 31
	v_writelane_b32 v254, s96, 32
	v_writelane_b32 v254, s97, 33
	v_writelane_b32 v254, s98, 34
	v_writelane_b32 v254, s99, 35
	v_readlane_b32 s0, v249, 62
	v_readlane_b32 s1, v248, 8
	s_cmp_eq_u32 s0, 1
	s_cbranch_scc0 .Lic1_c1
	s_cmp_eq_u32 s1, 0
	s_cbranch_scc1 .Lic1_c1
	s_mov_b32 s3, 0x11e4
	s_mov_b32 s101, 0x17bf
	s_mov_b32 s52, 0
	s_branch .Lic1_go
.Lic1_c1:
	s_cmp_eq_u32 s0, 1
	s_cbranch_scc0 .Lic1_c2
	s_cmp_eq_u32 s1, 0
	s_cbranch_scc0 .Lic1_c2
	s_mov_b32 s3, 0x580
	s_mov_b32 s101, 0xb5b
	s_mov_b32 s52, 1
	s_branch .Lic1_go
.Lic1_c2:
	s_cmp_eq_u32 s0, 2
	s_cbranch_scc0 .Lic1_c3
	s_cmp_eq_u32 s1, 0
	s_cbranch_scc1 .Lic1_c3
	s_mov_b32 s3, 0xb5c
	s_mov_b32 s101, 0x1137
	s_mov_b32 s52, 1
	s_branch .Lic1_go
.Lic1_c3:
	s_cmp_eq_u32 s0, 2
	s_cbranch_scc0 .Lic1_c4
	s_cmp_eq_u32 s1, 0
	s_cbranch_scc0 .Lic1_c4
	s_mov_b32 s3, 0x15e0
	s_mov_b32 s101, 0x17bf
	s_mov_b32 s52, 1
	s_branch .Lic1_go

.LnrmB_loop:
	s_mov_b32 s37, s36
	s_cmpk_gt_i32 s37, 0x207f
	s_cselect_b32 s43, 0x2080, 0
	s_cselect_b32 vcc_lo, 0x2000, 0
	s_cselect_b32 vcc_hi, 0x80, 0
	s_sub_i32 s43, s37, s43
	s_add_i32 vcc_lo, vcc_lo, s43
	s_addk_i32 vcc_lo, 0xff80
	s_add_i32 vcc_hi, vcc_hi, s43
	s_cmpk_lt_i32 s43, 0x80
	s_cselect_b32 vcc_lo, vcc_hi, vcc_lo
	s_cselect_b32 s0, s40, s92
	s_cselect_b32 s1, s41, s93
	s_lshl_b32 vcc_lo, vcc_lo, 12
	s_lshl_b32 vcc_hi, s37, 11
	v_add_u32_e32 v114, vcc_lo, v106
	v_add_u32_e32 v117, vcc_hi, v107
	global_load_dwordx2 v[16:17], v117, s[4:5] nt
	global_load_dwordx2 v[18:19], v117, s[4:5] offset:512 nt
	global_load_dwordx2 v[20:21], v117, s[4:5] offset:1024 nt
	global_load_dwordx2 v[22:23], v117, s[4:5] offset:1536 nt
	global_load_dwordx4 v[0:3], v114, s[0:1] nt
	global_load_dwordx4 v[4:7], v114, s[0:1] offset:1024 nt
	global_load_dwordx4 v[8:11], v114, s[0:1] offset:2048 nt
	global_load_dwordx4 v[12:15], v114, s[0:1] offset:3072 nt
	s_add_i32 s37, s36, s14
	s_cmpk_lt_i32 s37, 0x4100
	s_cselect_b32 s37, s37, s36
	s_cmpk_gt_i32 s37, 0x207f
	s_cselect_b32 s43, 0x2080, 0
	s_cselect_b32 vcc_lo, 0x2000, 0
	s_cselect_b32 vcc_hi, 0x80, 0
	s_sub_i32 s43, s37, s43
	s_add_i32 vcc_lo, vcc_lo, s43
	s_addk_i32 vcc_lo, 0xff80
	s_add_i32 vcc_hi, vcc_hi, s43
	s_cmpk_lt_i32 s43, 0x80
	s_cselect_b32 vcc_lo, vcc_hi, vcc_lo
	s_cselect_b32 s12, s40, s92
	s_cselect_b32 s13, s41, s93
	s_lshl_b32 vcc_lo, vcc_lo, 12
	s_lshl_b32 vcc_hi, s37, 11
	v_add_u32_e32 v115, vcc_lo, v106
	v_add_u32_e32 v118, vcc_hi, v107
	global_load_dwordx2 v[40:41], v118, s[4:5] nt
	global_load_dwordx2 v[42:43], v118, s[4:5] offset:512 nt
	global_load_dwordx2 v[44:45], v118, s[4:5] offset:1024 nt
	global_load_dwordx2 v[46:47], v118, s[4:5] offset:1536 nt
	global_load_dwordx4 v[24:27], v115, s[12:13] nt
	global_load_dwordx4 v[28:31], v115, s[12:13] offset:1024 nt
	global_load_dwordx4 v[32:35], v115, s[12:13] offset:2048 nt
	global_load_dwordx4 v[36:39], v115, s[12:13] offset:3072 nt
	s_lshl_b32 s37, s14, 1
	s_add_i32 s37, s36, s37
	s_cmpk_lt_i32 s37, 0x4100
	s_cselect_b32 s37, s37, s36
	s_cmpk_gt_i32 s37, 0x207f
	s_cselect_b32 s43, 0x2080, 0
	s_cselect_b32 vcc_lo, 0x2000, 0
	s_cselect_b32 vcc_hi, 0x80, 0
	s_sub_i32 s43, s37, s43
	s_add_i32 vcc_lo, vcc_lo, s43
	s_addk_i32 vcc_lo, 0xff80
	s_add_i32 vcc_hi, vcc_hi, s43
	s_cmpk_lt_i32 s43, 0x80
	s_cselect_b32 vcc_lo, vcc_hi, vcc_lo
	s_cselect_b32 s38, s40, s92
	s_cselect_b32 s39, s41, s93
	s_lshl_b32 vcc_lo, vcc_lo, 12
	s_lshl_b32 vcc_hi, s37, 11
	v_add_u32_e32 v116, vcc_lo, v106
	v_add_u32_e32 v119, vcc_hi, v107
	global_load_dwordx2 v[64:65], v119, s[4:5] nt
	global_load_dwordx2 v[66:67], v119, s[4:5] offset:512 nt
	global_load_dwordx2 v[68:69], v119, s[4:5] offset:1024 nt
	global_load_dwordx2 v[70:71], v119, s[4:5] offset:1536 nt
	global_load_dwordx4 v[48:51], v116, s[38:39] nt
	global_load_dwordx4 v[52:55], v116, s[38:39] offset:1024 nt
	global_load_dwordx4 v[56:59], v116, s[38:39] offset:2048 nt
	global_load_dwordx4 v[60:63], v116, s[38:39] offset:3072 nt
	s_waitcnt vmcnt(16)
	v_lshlrev_b32_e32 v120, 16, v16
	v_and_b32_e32 v16, 0xffff0000, v16
	v_lshlrev_b32_e32 v121, 16, v17
	v_and_b32_e32 v17, 0xffff0000, v17
	v_lshlrev_b32_e32 v122, 16, v18
	v_and_b32_e32 v18, 0xffff0000, v18
	v_lshlrev_b32_e32 v123, 16, v19
	v_and_b32_e32 v19, 0xffff0000, v19
	v_lshlrev_b32_e32 v124, 16, v20
	v_and_b32_e32 v20, 0xffff0000, v20
	v_lshlrev_b32_e32 v125, 16, v21
	v_and_b32_e32 v21, 0xffff0000, v21
	v_lshlrev_b32_e32 v126, 16, v22
	v_and_b32_e32 v22, 0xffff0000, v22
	v_lshlrev_b32_e32 v127, 16, v23
	v_and_b32_e32 v23, 0xffff0000, v23
	v_mul_f32_e32 v128, v16, v16
	v_mul_f32_e32 v129, v18, v18
	v_mul_f32_e32 v130, v20, v20
	v_mul_f32_e32 v131, v22, v22
	v_fmac_f32_e32 v128, v120, v120
	v_fmac_f32_e32 v129, v122, v122
	v_fmac_f32_e32 v130, v124, v124
	v_fmac_f32_e32 v131, v126, v126
	v_fmac_f32_e32 v128, v121, v121
	v_fmac_f32_e32 v129, v123, v123
	v_fmac_f32_e32 v130, v125, v125
	v_fmac_f32_e32 v131, v127, v127
	v_fmac_f32_e32 v128, v17, v17
	v_fmac_f32_e32 v129, v19, v19
	v_fmac_f32_e32 v130, v21, v21
	v_fmac_f32_e32 v131, v23, v23
	v_add_f32_e32 v132, v128, v129
	v_add_f32_e32 v132, v132, v130
	v_add_f32_e32 v132, v132, v131
	ds_bpermute_b32 v138, v108, v132
	s_waitcnt lgkmcnt(0)
	v_add_f32_e32 v132, v132, v138
	ds_bpermute_b32 v138, v109, v132
	s_waitcnt lgkmcnt(0)
	v_add_f32_e32 v132, v132, v138
	ds_bpermute_b32 v138, v110, v132
	s_waitcnt lgkmcnt(0)
	v_add_f32_e32 v132, v132, v138
	ds_bpermute_b32 v138, v111, v132
	s_waitcnt lgkmcnt(0)
	v_add_f32_e32 v132, v132, v138
	ds_bpermute_b32 v138, v112, v132
	s_waitcnt lgkmcnt(0)
	v_add_f32_e32 v132, v132, v138
	ds_bpermute_b32 v138, v113, v132
	s_waitcnt lgkmcnt(0)
	v_add_f32_e32 v132, v132, v138
	v_fmamk_f32 v132, v132, 0x3a800000, v177
	v_mov_b32_e32 v135, 0x800000
	v_cmp_gt_f32_e32 vcc, v135, v132
	v_mul_f32_e32 v133, 0x4b800000, v132
	s_nop 1
	v_cndmask_b32_e32 v132, v132, v133, vcc
	v_rsq_f32_e32 v132, v132
	s_nop 0
	v_mul_f32_e32 v133, 0x45800000, v132
	v_cndmask_b32_e32 v132, v132, v133, vcc
	v_mul_f32_e32 v134, 0.5, v132
	v_mul_f32_e32 v120, v72, v120
	v_mul_f32_e32 v16, v73, v16
	v_mul_f32_e32 v121, v74, v121
	v_mul_f32_e32 v17, v75, v17
	v_mul_f32_e32 v122, v76, v122
	v_mul_f32_e32 v18, v77, v18
	v_mul_f32_e32 v123, v78, v123
	v_mul_f32_e32 v19, v79, v19
	v_mul_f32_e32 v124, v80, v124
	v_mul_f32_e32 v20, v81, v20
	v_mul_f32_e32 v125, v82, v125
	v_mul_f32_e32 v21, v83, v21
	v_mul_f32_e32 v126, v84, v126
	v_mul_f32_e32 v22, v85, v22
	v_mul_f32_e32 v127, v86, v127
	v_mul_f32_e32 v23, v87, v23
	v_fmac_f32_e32 v0, v120, v134
	v_fmac_f32_e32 v1, v16, v134
	v_fmac_f32_e32 v2, v121, v134
	v_fmac_f32_e32 v3, v17, v134
	v_fmac_f32_e32 v4, v122, v134
	v_fmac_f32_e32 v5, v18, v134
	v_fmac_f32_e32 v6, v123, v134
	v_fmac_f32_e32 v7, v19, v134
	v_fmac_f32_e32 v8, v124, v134
	v_fmac_f32_e32 v9, v20, v134
	v_fmac_f32_e32 v10, v125, v134
	v_fmac_f32_e32 v11, v21, v134
	v_fmac_f32_e32 v12, v126, v134
	v_fmac_f32_e32 v13, v22, v134
	v_fmac_f32_e32 v14, v127, v134
	v_fmac_f32_e32 v15, v23, v134
	global_store_dwordx4 v114, v[0:3], s[0:1] nt
	global_store_dwordx4 v114, v[4:7], s[0:1] offset:1024 nt
	global_store_dwordx4 v114, v[8:11], s[0:1] offset:2048 nt
	global_store_dwordx4 v114, v[12:15], s[0:1] offset:3072 nt
	s_cmp_eq_u32 s42, 0
	s_cbranch_scc1 .LnrmB_nopre0
	v_mul_f32_e32 v128, v1, v1
	v_mul_f32_e32 v129, v5, v5
	v_mul_f32_e32 v130, v9, v9
	v_mul_f32_e32 v131, v13, v13
	v_fmac_f32_e32 v128, v0, v0
	v_fmac_f32_e32 v129, v4, v4
	v_fmac_f32_e32 v130, v8, v8
	v_fmac_f32_e32 v131, v12, v12
	v_fmac_f32_e32 v128, v2, v2
	v_fmac_f32_e32 v129, v6, v6
	v_fmac_f32_e32 v130, v10, v10
	v_fmac_f32_e32 v131, v14, v14
	v_fmac_f32_e32 v128, v3, v3
	v_fmac_f32_e32 v129, v7, v7
	v_fmac_f32_e32 v130, v11, v11
	v_fmac_f32_e32 v131, v15, v15
	v_add_f32_e32 v132, v128, v129
	v_add_f32_e32 v132, v130, v132
	v_add_f32_e32 v132, v131, v132
	ds_bpermute_b32 v138, v108, v132
	s_waitcnt lgkmcnt(0)
	v_add_f32_e32 v132, v132, v138
	ds_bpermute_b32 v138, v109, v132
	s_waitcnt lgkmcnt(0)
	v_add_f32_e32 v132, v132, v138
	ds_bpermute_b32 v138, v110, v132
	s_waitcnt lgkmcnt(0)
	v_add_f32_e32 v132, v132, v138
	ds_bpermute_b32 v138, v111, v132
	s_waitcnt lgkmcnt(0)
	v_add_f32_e32 v132, v132, v138
	ds_bpermute_b32 v138, v112, v132
	s_waitcnt lgkmcnt(0)
	v_add_f32_e32 v132, v132, v138
	ds_bpermute_b32 v138, v113, v132
	s_waitcnt lgkmcnt(0)
	v_add_f32_e32 v132, v132, v138
	v_fmamk_f32 v132, v132, 0x3a800000, v177
	v_mov_b32_e32 v135, 0x800000
	v_cmp_gt_f32_e32 vcc, v135, v132
	v_mul_f32_e32 v133, 0x4b800000, v132
	s_nop 1
	v_cndmask_b32_e32 v132, v132, v133, vcc
	v_rsq_f32_e32 v132, v132
	s_nop 0
	v_mul_f32_e32 v133, 0x45800000, v132
	v_cndmask_b32_e32 v134, v132, v133, vcc
	v_mul_f32_e32 v0, v0, v88
	v_mul_f32_e32 v1, v1, v89
	v_mul_f32_e32 v2, v2, v90
	v_mul_f32_e32 v3, v3, v91
	v_mul_f32_e32 v4, v4, v92
	v_mul_f32_e32 v5, v5, v93
	v_mul_f32_e32 v6, v6, v94
	v_mul_f32_e32 v7, v7, v95
	v_mul_f32_e32 v8, v8, v96
	v_mul_f32_e32 v9, v9, v97
	v_mul_f32_e32 v10, v10, v98
	v_mul_f32_e32 v11, v11, v99
	v_mul_f32_e32 v12, v12, v100
	v_mul_f32_e32 v13, v13, v101
	v_mul_f32_e32 v14, v14, v102
	v_mul_f32_e32 v15, v15, v103
	v_mul_f32_e32 v0, v0, v134
	v_mul_f32_e32 v1, v1, v134
	v_mul_f32_e32 v2, v2, v134
	v_mul_f32_e32 v3, v3, v134
	v_mul_f32_e32 v4, v4, v134
	v_mul_f32_e32 v5, v5, v134
	v_mul_f32_e32 v6, v6, v134
	v_mul_f32_e32 v7, v7, v134
	v_mul_f32_e32 v8, v8, v134
	v_mul_f32_e32 v9, v9, v134
	v_mul_f32_e32 v10, v10, v134
	v_mul_f32_e32 v11, v11, v134
	v_mul_f32_e32 v12, v12, v134
	v_mul_f32_e32 v13, v13, v134
	v_mul_f32_e32 v14, v14, v134
	v_mul_f32_e32 v15, v15, v134
	v_cvt_pk_bf16_f32 v120, v0, v1
	v_cvt_pk_bf16_f32 v121, v2, v3
	v_cvt_pk_bf16_f32 v122, v4, v5
	v_cvt_pk_bf16_f32 v123, v6, v7
	v_cvt_pk_bf16_f32 v124, v8, v9
	v_cvt_pk_bf16_f32 v125, v10, v11
	v_cvt_pk_bf16_f32 v126, v12, v13
	v_cvt_pk_bf16_f32 v127, v14, v15
	global_store_dwordx2 v117, v[120:121], s[4:5] nt
	global_store_dwordx2 v117, v[122:123], s[4:5] offset:512 nt
	global_store_dwordx2 v117, v[124:125], s[4:5] offset:1024 nt
	global_store_dwordx2 v117, v[126:127], s[4:5] offset:1536 nt
.LnrmB_nopre0:
	s_add_i32 s37, s36, s14
	s_cmpk_lt_i32 s37, 0x4100
	s_cbranch_scc0 .LnrmB_skip1
	s_waitcnt vmcnt(12)
	v_lshlrev_b32_e32 v120, 16, v40
	v_and_b32_e32 v40, 0xffff0000, v40
	v_lshlrev_b32_e32 v121, 16, v41
	v_and_b32_e32 v41, 0xffff0000, v41
	v_lshlrev_b32_e32 v122, 16, v42
	v_and_b32_e32 v42, 0xffff0000, v42
	v_lshlrev_b32_e32 v123, 16, v43
	v_and_b32_e32 v43, 0xffff0000, v43
	v_lshlrev_b32_e32 v124, 16, v44
	v_and_b32_e32 v44, 0xffff0000, v44
	v_lshlrev_b32_e32 v125, 16, v45
	v_and_b32_e32 v45, 0xffff0000, v45
	v_lshlrev_b32_e32 v126, 16, v46
	v_and_b32_e32 v46, 0xffff0000, v46
	v_lshlrev_b32_e32 v127, 16, v47
	v_and_b32_e32 v47, 0xffff0000, v47
	v_mul_f32_e32 v128, v40, v40
	v_mul_f32_e32 v129, v42, v42
	v_mul_f32_e32 v130, v44, v44
	v_mul_f32_e32 v131, v46, v46
	v_fmac_f32_e32 v128, v120, v120
	v_fmac_f32_e32 v129, v122, v122
	v_fmac_f32_e32 v130, v124, v124
	v_fmac_f32_e32 v131, v126, v126
	v_fmac_f32_e32 v128, v121, v121
	v_fmac_f32_e32 v129, v123, v123
	v_fmac_f32_e32 v130, v125, v125
	v_fmac_f32_e32 v131, v127, v127
	v_fmac_f32_e32 v128, v41, v41
	v_fmac_f32_e32 v129, v43, v43
	v_fmac_f32_e32 v130, v45, v45
	v_fmac_f32_e32 v131, v47, v47
	v_add_f32_e32 v132, v128, v129
	v_add_f32_e32 v132, v132, v130
	v_add_f32_e32 v132, v132, v131
	ds_bpermute_b32 v138, v108, v132
	s_waitcnt lgkmcnt(0)
	v_add_f32_e32 v132, v132, v138
	ds_bpermute_b32 v138, v109, v132
	s_waitcnt lgkmcnt(0)
	v_add_f32_e32 v132, v132, v138
	ds_bpermute_b32 v138, v110, v132
	s_waitcnt lgkmcnt(0)
	v_add_f32_e32 v132, v132, v138
	ds_bpermute_b32 v138, v111, v132
	s_waitcnt lgkmcnt(0)
	v_add_f32_e32 v132, v132, v138
	ds_bpermute_b32 v138, v112, v132
	s_waitcnt lgkmcnt(0)
	v_add_f32_e32 v132, v132, v138
	ds_bpermute_b32 v138, v113, v132
	s_waitcnt lgkmcnt(0)
	v_add_f32_e32 v132, v132, v138
	v_fmamk_f32 v132, v132, 0x3a800000, v177
	v_mov_b32_e32 v135, 0x800000
	v_cmp_gt_f32_e32 vcc, v135, v132
	v_mul_f32_e32 v133, 0x4b800000, v132
	s_nop 1
	v_cndmask_b32_e32 v132, v132, v133, vcc
	v_rsq_f32_e32 v132, v132
	s_nop 0
	v_mul_f32_e32 v133, 0x45800000, v132
	v_cndmask_b32_e32 v132, v132, v133, vcc
	v_mul_f32_e32 v134, 0.5, v132
	v_mul_f32_e32 v120, v72, v120
	v_mul_f32_e32 v40, v73, v40
	v_mul_f32_e32 v121, v74, v121
	v_mul_f32_e32 v41, v75, v41
	v_mul_f32_e32 v122, v76, v122
	v_mul_f32_e32 v42, v77, v42
	v_mul_f32_e32 v123, v78, v123
	v_mul_f32_e32 v43, v79, v43
	v_mul_f32_e32 v124, v80, v124
	v_mul_f32_e32 v44, v81, v44
	v_mul_f32_e32 v125, v82, v125
	v_mul_f32_e32 v45, v83, v45
	v_mul_f32_e32 v126, v84, v126
	v_mul_f32_e32 v46, v85, v46
	v_mul_f32_e32 v127, v86, v127
	v_mul_f32_e32 v47, v87, v47
	v_fmac_f32_e32 v24, v120, v134
	v_fmac_f32_e32 v25, v40, v134
	v_fmac_f32_e32 v26, v121, v134
	v_fmac_f32_e32 v27, v41, v134
	v_fmac_f32_e32 v28, v122, v134
	v_fmac_f32_e32 v29, v42, v134
	v_fmac_f32_e32 v30, v123, v134
	v_fmac_f32_e32 v31, v43, v134
	v_fmac_f32_e32 v32, v124, v134
	v_fmac_f32_e32 v33, v44, v134
	v_fmac_f32_e32 v34, v125, v134
	v_fmac_f32_e32 v35, v45, v134
	v_fmac_f32_e32 v36, v126, v134
	v_fmac_f32_e32 v37, v46, v134
	v_fmac_f32_e32 v38, v127, v134
	v_fmac_f32_e32 v39, v47, v134
	global_store_dwordx4 v115, v[24:27], s[12:13] nt
	global_store_dwordx4 v115, v[28:31], s[12:13] offset:1024 nt
	global_store_dwordx4 v115, v[32:35], s[12:13] offset:2048 nt
	global_store_dwordx4 v115, v[36:39], s[12:13] offset:3072 nt
	s_cmp_eq_u32 s42, 0
	s_cbranch_scc1 .LnrmB_skip1
	v_mul_f32_e32 v128, v25, v25
	v_mul_f32_e32 v129, v29, v29
	v_mul_f32_e32 v130, v33, v33
	v_mul_f32_e32 v131, v37, v37
	v_fmac_f32_e32 v128, v24, v24
	v_fmac_f32_e32 v129, v28, v28
	v_fmac_f32_e32 v130, v32, v32
	v_fmac_f32_e32 v131, v36, v36
	v_fmac_f32_e32 v128, v26, v26
	v_fmac_f32_e32 v129, v30, v30
	v_fmac_f32_e32 v130, v34, v34
	v_fmac_f32_e32 v131, v38, v38
	v_fmac_f32_e32 v128, v27, v27
	v_fmac_f32_e32 v129, v31, v31
	v_fmac_f32_e32 v130, v35, v35
	v_fmac_f32_e32 v131, v39, v39
	v_add_f32_e32 v132, v128, v129
	v_add_f32_e32 v132, v130, v132
	v_add_f32_e32 v132, v131, v132
	ds_bpermute_b32 v138, v108, v132
	s_waitcnt lgkmcnt(0)
	v_add_f32_e32 v132, v132, v138
	ds_bpermute_b32 v138, v109, v132
	s_waitcnt lgkmcnt(0)
	v_add_f32_e32 v132, v132, v138
	ds_bpermute_b32 v138, v110, v132
	s_waitcnt lgkmcnt(0)
	v_add_f32_e32 v132, v132, v138
	ds_bpermute_b32 v138, v111, v132
	s_waitcnt lgkmcnt(0)
	v_add_f32_e32 v132, v132, v138
	ds_bpermute_b32 v138, v112, v132
	s_waitcnt lgkmcnt(0)
	v_add_f32_e32 v132, v132, v138
	ds_bpermute_b32 v138, v113, v132
	s_waitcnt lgkmcnt(0)
	v_add_f32_e32 v132, v132, v138
	v_fmamk_f32 v132, v132, 0x3a800000, v177
	v_mov_b32_e32 v135, 0x800000
	v_cmp_gt_f32_e32 vcc, v135, v132
	v_mul_f32_e32 v133, 0x4b800000, v132
	s_nop 1
	v_cndmask_b32_e32 v132, v132, v133, vcc
	v_rsq_f32_e32 v132, v132
	s_nop 0
	v_mul_f32_e32 v133, 0x45800000, v132
	v_cndmask_b32_e32 v134, v132, v133, vcc
	v_mul_f32_e32 v24, v24, v88
	v_mul_f32_e32 v25, v25, v89
	v_mul_f32_e32 v26, v26, v90
	v_mul_f32_e32 v27, v27, v91
	v_mul_f32_e32 v28, v28, v92
	v_mul_f32_e32 v29, v29, v93
	v_mul_f32_e32 v30, v30, v94
	v_mul_f32_e32 v31, v31, v95
	v_mul_f32_e32 v32, v32, v96
	v_mul_f32_e32 v33, v33, v97
	v_mul_f32_e32 v34, v34, v98
	v_mul_f32_e32 v35, v35, v99
	v_mul_f32_e32 v36, v36, v100
	v_mul_f32_e32 v37, v37, v101
	v_mul_f32_e32 v38, v38, v102
	v_mul_f32_e32 v39, v39, v103
	v_mul_f32_e32 v24, v24, v134
	v_mul_f32_e32 v25, v25, v134
	v_mul_f32_e32 v26, v26, v134
	v_mul_f32_e32 v27, v27, v134
	v_mul_f32_e32 v28, v28, v134
	v_mul_f32_e32 v29, v29, v134
	v_mul_f32_e32 v30, v30, v134
	v_mul_f32_e32 v31, v31, v134
	v_mul_f32_e32 v32, v32, v134
	v_mul_f32_e32 v33, v33, v134
	v_mul_f32_e32 v34, v34, v134
	v_mul_f32_e32 v35, v35, v134
	v_mul_f32_e32 v36, v36, v134
	v_mul_f32_e32 v37, v37, v134
	v_mul_f32_e32 v38, v38, v134
	v_mul_f32_e32 v39, v39, v134
	v_cvt_pk_bf16_f32 v120, v24, v25
	v_cvt_pk_bf16_f32 v121, v26, v27
	v_cvt_pk_bf16_f32 v122, v28, v29
	v_cvt_pk_bf16_f32 v123, v30, v31
	v_cvt_pk_bf16_f32 v124, v32, v33
	v_cvt_pk_bf16_f32 v125, v34, v35
	v_cvt_pk_bf16_f32 v126, v36, v37
	v_cvt_pk_bf16_f32 v127, v38, v39
	global_store_dwordx2 v118, v[120:121], s[4:5] nt
	global_store_dwordx2 v118, v[122:123], s[4:5] offset:512 nt
	global_store_dwordx2 v118, v[124:125], s[4:5] offset:1024 nt
	global_store_dwordx2 v118, v[126:127], s[4:5] offset:1536 nt
.LnrmB_skip1:
	s_lshl_b32 s37, s14, 1
	s_add_i32 s37, s36, s37
	s_cmpk_lt_i32 s37, 0x4100
	s_cbranch_scc0 .LnrmB_skip2
	s_waitcnt vmcnt(8)
	v_lshlrev_b32_e32 v120, 16, v64
	v_and_b32_e32 v64, 0xffff0000, v64
	v_lshlrev_b32_e32 v121, 16, v65
	v_and_b32_e32 v65, 0xffff0000, v65
	v_lshlrev_b32_e32 v122, 16, v66
	v_and_b32_e32 v66, 0xffff0000, v66
	v_lshlrev_b32_e32 v123, 16, v67
	v_and_b32_e32 v67, 0xffff0000, v67
	v_lshlrev_b32_e32 v124, 16, v68
	v_and_b32_e32 v68, 0xffff0000, v68
	v_lshlrev_b32_e32 v125, 16, v69
	v_and_b32_e32 v69, 0xffff0000, v69
	v_lshlrev_b32_e32 v126, 16, v70
	v_and_b32_e32 v70, 0xffff0000, v70
	v_lshlrev_b32_e32 v127, 16, v71
	v_and_b32_e32 v71, 0xffff0000, v71
	v_mul_f32_e32 v128, v64, v64
	v_mul_f32_e32 v129, v66, v66
	v_mul_f32_e32 v130, v68, v68
	v_mul_f32_e32 v131, v70, v70
	v_fmac_f32_e32 v128, v120, v120
	v_fmac_f32_e32 v129, v122, v122
	v_fmac_f32_e32 v130, v124, v124
	v_fmac_f32_e32 v131, v126, v126
	v_fmac_f32_e32 v128, v121, v121
	v_fmac_f32_e32 v129, v123, v123
	v_fmac_f32_e32 v130, v125, v125
	v_fmac_f32_e32 v131, v127, v127
	v_fmac_f32_e32 v128, v65, v65
	v_fmac_f32_e32 v129, v67, v67
	v_fmac_f32_e32 v130, v69, v69
	v_fmac_f32_e32 v131, v71, v71
	v_add_f32_e32 v132, v128, v129
	v_add_f32_e32 v132, v132, v130
	v_add_f32_e32 v132, v132, v131
	ds_bpermute_b32 v138, v108, v132
	s_waitcnt lgkmcnt(0)
	v_add_f32_e32 v132, v132, v138
	ds_bpermute_b32 v138, v109, v132
	s_waitcnt lgkmcnt(0)
	v_add_f32_e32 v132, v132, v138
	ds_bpermute_b32 v138, v110, v132
	s_waitcnt lgkmcnt(0)
	v_add_f32_e32 v132, v132, v138
	ds_bpermute_b32 v138, v111, v132
	s_waitcnt lgkmcnt(0)
	v_add_f32_e32 v132, v132, v138
	ds_bpermute_b32 v138, v112, v132
	s_waitcnt lgkmcnt(0)
	v_add_f32_e32 v132, v132, v138
	ds_bpermute_b32 v138, v113, v132
	s_waitcnt lgkmcnt(0)
	v_add_f32_e32 v132, v132, v138
	v_fmamk_f32 v132, v132, 0x3a800000, v177
	v_mov_b32_e32 v135, 0x800000
	v_cmp_gt_f32_e32 vcc, v135, v132
	v_mul_f32_e32 v133, 0x4b800000, v132
	s_nop 1
	v_cndmask_b32_e32 v132, v132, v133, vcc
	v_rsq_f32_e32 v132, v132
	s_nop 0
	v_mul_f32_e32 v133, 0x45800000, v132
	v_cndmask_b32_e32 v132, v132, v133, vcc
	v_mul_f32_e32 v134, 0.5, v132
	v_mul_f32_e32 v120, v72, v120
	v_mul_f32_e32 v64, v73, v64
	v_mul_f32_e32 v121, v74, v121
	v_mul_f32_e32 v65, v75, v65
	v_mul_f32_e32 v122, v76, v122
	v_mul_f32_e32 v66, v77, v66
	v_mul_f32_e32 v123, v78, v123
	v_mul_f32_e32 v67, v79, v67
	v_mul_f32_e32 v124, v80, v124
	v_mul_f32_e32 v68, v81, v68
	v_mul_f32_e32 v125, v82, v125
	v_mul_f32_e32 v69, v83, v69
	v_mul_f32_e32 v126, v84, v126
	v_mul_f32_e32 v70, v85, v70
	v_mul_f32_e32 v127, v86, v127
	v_mul_f32_e32 v71, v87, v71
	v_fmac_f32_e32 v48, v120, v134
	v_fmac_f32_e32 v49, v64, v134
	v_fmac_f32_e32 v50, v121, v134
	v_fmac_f32_e32 v51, v65, v134
	v_fmac_f32_e32 v52, v122, v134
	v_fmac_f32_e32 v53, v66, v134
	v_fmac_f32_e32 v54, v123, v134
	v_fmac_f32_e32 v55, v67, v134
	v_fmac_f32_e32 v56, v124, v134
	v_fmac_f32_e32 v57, v68, v134
	v_fmac_f32_e32 v58, v125, v134
	v_fmac_f32_e32 v59, v69, v134
	v_fmac_f32_e32 v60, v126, v134
	v_fmac_f32_e32 v61, v70, v134
	v_fmac_f32_e32 v62, v127, v134
	v_fmac_f32_e32 v63, v71, v134
	global_store_dwordx4 v116, v[48:51], s[38:39] nt
	global_store_dwordx4 v116, v[52:55], s[38:39] offset:1024 nt
	global_store_dwordx4 v116, v[56:59], s[38:39] offset:2048 nt
	global_store_dwordx4 v116, v[60:63], s[38:39] offset:3072 nt
	s_cmp_eq_u32 s42, 0
	s_cbranch_scc1 .LnrmB_skip2
	v_mul_f32_e32 v128, v49, v49
	v_mul_f32_e32 v129, v53, v53
	v_mul_f32_e32 v130, v57, v57
	v_mul_f32_e32 v131, v61, v61
	v_fmac_f32_e32 v128, v48, v48
	v_fmac_f32_e32 v129, v52, v52
	v_fmac_f32_e32 v130, v56, v56
	v_fmac_f32_e32 v131, v60, v60
	v_fmac_f32_e32 v128, v50, v50
	v_fmac_f32_e32 v129, v54, v54
	v_fmac_f32_e32 v130, v58, v58
	v_fmac_f32_e32 v131, v62, v62
	v_fmac_f32_e32 v128, v51, v51
	v_fmac_f32_e32 v129, v55, v55
	v_fmac_f32_e32 v130, v59, v59
	v_fmac_f32_e32 v131, v63, v63
	v_add_f32_e32 v132, v128, v129
	v_add_f32_e32 v132, v130, v132
	v_add_f32_e32 v132, v131, v132
	ds_bpermute_b32 v138, v108, v132
	s_waitcnt lgkmcnt(0)
	v_add_f32_e32 v132, v132, v138
	ds_bpermute_b32 v138, v109, v132
	s_waitcnt lgkmcnt(0)
	v_add_f32_e32 v132, v132, v138
	ds_bpermute_b32 v138, v110, v132
	s_waitcnt lgkmcnt(0)
	v_add_f32_e32 v132, v132, v138
	ds_bpermute_b32 v138, v111, v132
	s_waitcnt lgkmcnt(0)
	v_add_f32_e32 v132, v132, v138
	ds_bpermute_b32 v138, v112, v132
	s_waitcnt lgkmcnt(0)
	v_add_f32_e32 v132, v132, v138
	ds_bpermute_b32 v138, v113, v132
	s_waitcnt lgkmcnt(0)
	v_add_f32_e32 v132, v132, v138
	v_fmamk_f32 v132, v132, 0x3a800000, v177
	v_mov_b32_e32 v135, 0x800000
	v_cmp_gt_f32_e32 vcc, v135, v132
	v_mul_f32_e32 v133, 0x4b800000, v132
	s_nop 1
	v_cndmask_b32_e32 v132, v132, v133, vcc
	v_rsq_f32_e32 v132, v132
	s_nop 0
	v_mul_f32_e32 v133, 0x45800000, v132
	v_cndmask_b32_e32 v134, v132, v133, vcc
	v_mul_f32_e32 v48, v48, v88
	v_mul_f32_e32 v49, v49, v89
	v_mul_f32_e32 v50, v50, v90
	v_mul_f32_e32 v51, v51, v91
	v_mul_f32_e32 v52, v52, v92
	v_mul_f32_e32 v53, v53, v93
	v_mul_f32_e32 v54, v54, v94
	v_mul_f32_e32 v55, v55, v95
	v_mul_f32_e32 v56, v56, v96
	v_mul_f32_e32 v57, v57, v97
	v_mul_f32_e32 v58, v58, v98
	v_mul_f32_e32 v59, v59, v99
	v_mul_f32_e32 v60, v60, v100
	v_mul_f32_e32 v61, v61, v101
	v_mul_f32_e32 v62, v62, v102
	v_mul_f32_e32 v63, v63, v103
	v_mul_f32_e32 v48, v48, v134
	v_mul_f32_e32 v49, v49, v134
	v_mul_f32_e32 v50, v50, v134
	v_mul_f32_e32 v51, v51, v134
	v_mul_f32_e32 v52, v52, v134
	v_mul_f32_e32 v53, v53, v134
	v_mul_f32_e32 v54, v54, v134
	v_mul_f32_e32 v55, v55, v134
	v_mul_f32_e32 v56, v56, v134
	v_mul_f32_e32 v57, v57, v134
	v_mul_f32_e32 v58, v58, v134
	v_mul_f32_e32 v59, v59, v134
	v_mul_f32_e32 v60, v60, v134
	v_mul_f32_e32 v61, v61, v134
	v_mul_f32_e32 v62, v62, v134
	v_mul_f32_e32 v63, v63, v134
	v_cvt_pk_bf16_f32 v120, v48, v49
	v_cvt_pk_bf16_f32 v121, v50, v51
	v_cvt_pk_bf16_f32 v122, v52, v53
	v_cvt_pk_bf16_f32 v123, v54, v55
	v_cvt_pk_bf16_f32 v124, v56, v57
	v_cvt_pk_bf16_f32 v125, v58, v59
	v_cvt_pk_bf16_f32 v126, v60, v61
	v_cvt_pk_bf16_f32 v127, v62, v63
	global_store_dwordx2 v119, v[120:121], s[4:5] nt
	global_store_dwordx2 v119, v[122:123], s[4:5] offset:512 nt
	global_store_dwordx2 v119, v[124:125], s[4:5] offset:1024 nt
	global_store_dwordx2 v119, v[126:127], s[4:5] offset:1536 nt

.LBB0_1658:
	s_cmp_lg_u32 s52, 2
	s_cselect_b64 s[0:1], -1, 0
	v_writelane_b32 v249, s0, 49
	s_cmp_eq_u32 s96, 0x100
	s_cselect_b32 s100, 1, 2
	s_cmp_ge_u32 s52, s100
	s_nop 0
	v_writelane_b32 v249, s1, 50
	s_cbranch_scc1 .LBB0_1765
	v_writelane_b32 v255, s2, 0
	v_writelane_b32 v255, 0, 1
	s_movk_i32 s101, 0x17bf
	s_cmp_eq_u32 s96, 0x100
	s_cmovk_i32 s101, 0x11e3
	s_mov_b32 s100, s96
	v_readlane_b32 s0, v252, 52
	v_readlane_b32 s1, v252, 53
	v_mov_b32_e32 v12, v136
	s_waitcnt vmcnt(0)
	v_mov_b32_e32 v3, 0
	v_cndmask_b32_e64 v0, 0, 1, s[0:1]
	v_cmp_ne_u32_e64 s[36:37], 1, v0
	v_ashrrev_i32_e32 v11, 3, v12
	s_andn2_b64 vcc, exec, s[0:1]
	v_mov_b32_e32 v2, v3
	v_mov_b32_e32 v1, v3
	v_mov_b32_e32 v0, v3
	v_mov_b32_e32 v7, v3
	v_mov_b32_e32 v6, v3
	v_mov_b32_e32 v5, v3
	v_mov_b32_e32 v4, v3
	s_cbranch_vccnz .LBB0_1711
	v_readlane_b32 s0, v252, 54
	v_readlane_b32 s1, v252, 55
	s_mov_b64 s[20:21], -1
	s_and_b64 vcc, exec, s[0:1]
	s_cbranch_vccz .LBB0_1670
	v_readlane_b32 s0, v252, 56
	v_readlane_b32 s1, v252, 57
	s_and_b64 vcc, exec, s[0:1]
	s_cbranch_vccz .LBB0_1685
	v_readlane_b32 s0, v252, 58
	v_readlane_b32 s1, v252, 59
	s_and_b64 vcc, exec, s[0:1]
	s_cbranch_vccz .LBB0_1682
	v_readlane_b32 s0, v252, 60
	v_readlane_b32 s1, v252, 61
	s_and_b64 vcc, exec, s[0:1]
	s_cbranch_vccz .LBB0_1679
	v_readlane_b32 s0, v252, 62
	v_readlane_b32 s1, v252, 63
	s_and_b64 vcc, exec, s[0:1]
	s_cbranch_vccz .LBB0_1676
	v_readlane_b32 s0, v250, 0
	v_readlane_b32 s1, v250, 1
	s_and_b64 vcc, exec, s[0:1]
	s_cbranch_vccz .LBB0_1673
	v_readlane_b32 s0, v250, 2
	v_readlane_b32 s1, v250, 3
	s_mov_b64 s[12:13], -1
	s_and_b64 vcc, exec, s[0:1]
	s_cbranch_vccz .LBB0_1668
	v_readlane_b32 s56, v251, 24
	s_mul_i32 s0, s52, 0xb00000
	v_readlane_b32 s66, v251, 34
	s_mul_hi_u32 s1, s52, 0xb00000
	v_readlane_b32 s67, v251, 35
	s_add_u32 s0, s66, s0
	v_readlane_b32 s57, v251, 25
	v_readlane_b32 s58, v251, 26
	v_readlane_b32 s59, v251, 27
	v_readlane_b32 s60, v251, 28
	v_readlane_b32 s61, v251, 29
	v_readlane_b32 s62, v251, 30
	v_readlane_b32 s63, v251, 31
	v_readlane_b32 s64, v251, 32
	v_readlane_b32 s65, v251, 33
	v_readlane_b32 s68, v251, 36
	v_readlane_b32 s69, v251, 37
	v_readlane_b32 s70, v251, 38
	v_readlane_b32 s71, v251, 39
	s_addc_u32 s1, s67, s1
	s_mov_b64 s[12:13], 0
